# P1 bias rows rewritten: all weight-row and shift-vector loads issued up front, dot products from registers, DPP-only wave sums
# speedup vs baseline: 1.0190x; 1.0045x over previous
; __device__ __forceinline__ void p1_rows(const Args& A, int lane, int wave) {
;     ...
;     for (int it = gw; it < DIN + NGU; it += NGW) {
;         const bool second = it >= DIN; const int dr = second ? it - DIN : it;
;         const bf16_t* wrow = (const bf16_t*)(ws + (second ? WS_W2GU : WS_WIN)) + (size_t)dr * DM;
;         const float* sh = mods + (second ? MOD_SH3 : MOD_SH2) * DM;
;         float a0 = 0.f, a1 = 0.f, a2 = 0.f, a3 = 0.f;
; #pragma unroll
;         for (int j = 0; j < 2; ++j) { const int k = 8 * lane + 512 * j; f32x4 wa, wb; pg8::unpack8(*(const u32x4*)(wrow + k), wa, wb);
;     ...
;             BDOT(a0, 0) BDOT(a1, 1) BDOT(a2, 2) BDOT(a3, 3)
.LBB0_143:
	s_cmpk_gt_i32 s6, 0x2fff
	s_cbranch_scc1 .LBB0_148
	s_waitcnt lgkmcnt(0)
	v_lshlrev_b32_e32 v11, 1, v34
	v_lshlrev_b32_e32 v32, 2, v34
	s_mov_b32 s14, 0x2d00000
	s_mov_b32 s15, 0x1a00000
	s_mov_b32 s0, s6
	s_add_i32 s9, s0, 0xffffe600
	s_cmpk_gt_i32 s0, 0x19ff
	s_cselect_b32 s9, s9, s0
	s_cselect_b32 s1, s14, s15
	s_lshl_b32 s9, s9, 11
	s_add_u32 s12, s4, s1
	s_addc_u32 s13, s5, 0
	s_add_u32 s12, s12, s9
	s_addc_u32 s13, s13, 0
	global_load_dwordx4 v[40:43], v11, s[12:13]
	global_load_dwordx4 v[44:47], v11, s[12:13] offset:1024
	s_add_i32 s0, s0, s8
	s_add_i32 s9, s0, 0xffffe600
	s_cmpk_gt_i32 s0, 0x19ff
	s_cselect_b32 s9, s9, s0
	s_cselect_b32 s1, s14, s15
	s_lshl_b32 s9, s9, 11
	s_add_u32 s12, s4, s1
	s_addc_u32 s13, s5, 0
	s_add_u32 s12, s12, s9
	s_addc_u32 s13, s13, 0
	global_load_dwordx4 v[48:51], v11, s[12:13]
	global_load_dwordx4 v[52:55], v11, s[12:13] offset:1024
	s_add_i32 s0, s0, s8
	s_add_i32 s9, s0, 0xffffe600
	s_cmpk_gt_i32 s0, 0x19ff
	s_cselect_b32 s9, s9, s0
	s_cselect_b32 s1, s14, s15
	s_lshl_b32 s9, s9, 11
	s_add_u32 s12, s4, s1
	s_addc_u32 s13, s5, 0
	s_add_u32 s12, s12, s9
	s_addc_u32 s13, s13, 0
	global_load_dwordx4 v[56:59], v11, s[12:13]
	global_load_dwordx4 v[60:63], v11, s[12:13] offset:1024
	s_add_i32 s0, s0, s8
	s_add_i32 s9, s0, 0xffffe600
	s_cmpk_gt_i32 s0, 0x19ff
	s_cselect_b32 s9, s9, s0
	s_cselect_b32 s1, s14, s15
	s_lshl_b32 s9, s9, 11
	s_add_u32 s12, s4, s1
	s_addc_u32 s13, s5, 0
	s_add_u32 s12, s12, s9
	s_addc_u32 s13, s13, 0
	global_load_dwordx4 v[64:67], v11, s[12:13]
	global_load_dwordx4 v[68:71], v11, s[12:13] offset:1024
	s_add_i32 s0, s0, s8
	s_add_i32 s9, s0, 0xffffe600
	s_cmpk_gt_i32 s0, 0x19ff
	s_cselect_b32 s9, s9, s0
	s_cselect_b32 s1, s14, s15
	s_lshl_b32 s9, s9, 11
	s_add_u32 s12, s4, s1
	s_addc_u32 s13, s5, 0
	s_add_u32 s12, s12, s9
	s_addc_u32 s13, s13, 0
	global_load_dwordx4 v[72:75], v11, s[12:13]
	global_load_dwordx4 v[76:79], v11, s[12:13] offset:1024
	s_add_i32 s0, s0, s8
	s_add_i32 s9, s0, 0xffffe600
	s_cmpk_gt_i32 s0, 0x19ff
	s_cselect_b32 s9, s9, s0
	s_cselect_b32 s1, s14, s15
	s_lshl_b32 s9, s9, 11
	s_add_u32 s12, s4, s1
	s_addc_u32 s13, s5, 0
	s_add_u32 s12, s12, s9
	s_addc_u32 s13, s13, 0
	global_load_dwordx4 v[80:83], v11, s[12:13]
	global_load_dwordx4 v[84:87], v11, s[12:13] offset:1024
	s_add_u32 s16, s4, 0x3000
	s_addc_u32 s17, s5, 0
	global_load_dwordx4 v[100:103], v32, s[16:17]
	global_load_dwordx4 v[104:107], v32, s[16:17] offset:16
	global_load_dwordx4 v[108:111], v32, s[16:17] offset:2048
	global_load_dwordx4 v[112:115], v32, s[16:17] offset:2064
	s_add_u32 s16, s16, 0x9000
	s_addc_u32 s17, s17, 0
	global_load_dwordx4 v[116:119], v32, s[16:17]
	global_load_dwordx4 v[120:123], v32, s[16:17] offset:16
	global_load_dwordx4 v[124:127], v32, s[16:17] offset:2048
	global_load_dwordx4 v[128:131], v32, s[16:17] offset:2064
	s_add_u32 s16, s16, 0x9000
	s_addc_u32 s17, s17, 0
	global_load_dwordx4 v[132:135], v32, s[16:17]
	global_load_dwordx4 v[136:139], v32, s[16:17] offset:16
	global_load_dwordx4 v[140:143], v32, s[16:17] offset:2048
	global_load_dwordx4 v[144:147], v32, s[16:17] offset:2064
	s_add_u32 s16, s16, 0x9000
	s_addc_u32 s17, s17, 0
	global_load_dwordx4 v[148:151], v32, s[16:17]
	global_load_dwordx4 v[152:155], v32, s[16:17] offset:16
	global_load_dwordx4 v[156:159], v32, s[16:17] offset:2048
	global_load_dwordx4 v[160:163], v32, s[16:17] offset:2064
	s_add_u32 s16, s4, 0x6000
	s_addc_u32 s17, s5, 0
	global_load_dwordx4 v[164:167], v32, s[16:17]
	global_load_dwordx4 v[168:171], v32, s[16:17] offset:16
	global_load_dwordx4 v[172:175], v32, s[16:17] offset:2048
	global_load_dwordx4 v[176:179], v32, s[16:17] offset:2064
	s_add_u32 s16, s16, 0x9000
	s_addc_u32 s17, s17, 0
	global_load_dwordx4 v[180:183], v32, s[16:17]
	global_load_dwordx4 v[184:187], v32, s[16:17] offset:16
	global_load_dwordx4 v[188:191], v32, s[16:17] offset:2048
	global_load_dwordx4 v[192:195], v32, s[16:17] offset:2064
	s_add_u32 s16, s16, 0x9000
	s_addc_u32 s17, s17, 0
	global_load_dwordx4 v[196:199], v32, s[16:17]
	global_load_dwordx4 v[200:203], v32, s[16:17] offset:16
	global_load_dwordx4 v[204:207], v32, s[16:17] offset:2048
	global_load_dwordx4 v[208:211], v32, s[16:17] offset:2064
	s_add_u32 s16, s16, 0x9000
	s_addc_u32 s17, s17, 0
	global_load_dwordx4 v[212:215], v32, s[16:17]
	global_load_dwordx4 v[216:219], v32, s[16:17] offset:16
	global_load_dwordx4 v[88:91], v32, s[16:17] offset:2048
	global_load_dwordx4 v[92:95], v32, s[16:17] offset:2064
	s_waitcnt vmcnt(16)
; __device__ __forceinline__ void p1_rows(const Args& A, int lane, int wave) {
;     ...
;         float a0 = 0.f, a1 = 0.f, a2 = 0.f, a3 = 0.f;
; #pragma unroll
;         for (int j = 0; j < 2; ++j) { const int k = 8 * lane + 512 * j; f32x4 wa, wb; pg8::unpack8(*(const u32x4*)(wrow + k), wa, wb);
;     ...
;             BDOT(a0, 0) BDOT(a1, 1) BDOT(a2, 2) BDOT(a3, 3)
;     ...
;         }
;         a0 = wave_sum(a0); a1 = wave_sum(a1); a2 = wave_sum(a2); a3 = wave_sum(a3);
	v_lshlrev_b32_e32 v12, 16, v40
	v_and_b32_e32 v13, 0xffff0000, v40
	v_lshlrev_b32_e32 v14, 16, v41
	v_and_b32_e32 v15, 0xffff0000, v41
	v_lshlrev_b32_e32 v16, 16, v42
	v_and_b32_e32 v17, 0xffff0000, v42
	v_lshlrev_b32_e32 v18, 16, v43
	v_and_b32_e32 v19, 0xffff0000, v43
	v_lshlrev_b32_e32 v20, 16, v44
	v_and_b32_e32 v21, 0xffff0000, v44
	v_lshlrev_b32_e32 v22, 16, v45
	v_and_b32_e32 v23, 0xffff0000, v45
	v_lshlrev_b32_e32 v24, 16, v46
	v_and_b32_e32 v25, 0xffff0000, v46
	v_lshlrev_b32_e32 v26, 16, v47
	v_and_b32_e32 v27, 0xffff0000, v47
	v_mul_f32_e32 v228, v12, v100
	v_mul_f32_e32 v229, v12, v116
	v_mul_f32_e32 v230, v12, v132
	v_mul_f32_e32 v231, v12, v148
	v_fmac_f32_e32 v228, v13, v101
	v_fmac_f32_e32 v229, v13, v117
	v_fmac_f32_e32 v230, v13, v133
	v_fmac_f32_e32 v231, v13, v149
	v_fmac_f32_e32 v228, v14, v102
	v_fmac_f32_e32 v229, v14, v118
	v_fmac_f32_e32 v230, v14, v134
	v_fmac_f32_e32 v231, v14, v150
	v_fmac_f32_e32 v228, v15, v103
	v_fmac_f32_e32 v229, v15, v119
	v_fmac_f32_e32 v230, v15, v135
	v_fmac_f32_e32 v231, v15, v151
	v_fmac_f32_e32 v228, v16, v104
	v_fmac_f32_e32 v229, v16, v120
	v_fmac_f32_e32 v230, v16, v136
	v_fmac_f32_e32 v231, v16, v152
	v_fmac_f32_e32 v228, v17, v105
	v_fmac_f32_e32 v229, v17, v121
	v_fmac_f32_e32 v230, v17, v137
	v_fmac_f32_e32 v231, v17, v153
	v_fmac_f32_e32 v228, v18, v106
	v_fmac_f32_e32 v229, v18, v122
	v_fmac_f32_e32 v230, v18, v138
	v_fmac_f32_e32 v231, v18, v154
	v_fmac_f32_e32 v228, v19, v107
	v_fmac_f32_e32 v229, v19, v123
	v_fmac_f32_e32 v230, v19, v139
	v_fmac_f32_e32 v231, v19, v155
	v_fmac_f32_e32 v228, v20, v108
	v_fmac_f32_e32 v229, v20, v124
	v_fmac_f32_e32 v230, v20, v140
	v_fmac_f32_e32 v231, v20, v156
	v_fmac_f32_e32 v228, v21, v109
	v_fmac_f32_e32 v229, v21, v125
	v_fmac_f32_e32 v230, v21, v141
	v_fmac_f32_e32 v231, v21, v157
	v_fmac_f32_e32 v228, v22, v110
	v_fmac_f32_e32 v229, v22, v126
	v_fmac_f32_e32 v230, v22, v142
	v_fmac_f32_e32 v231, v22, v158
	v_fmac_f32_e32 v228, v23, v111
	v_fmac_f32_e32 v229, v23, v127
	v_fmac_f32_e32 v230, v23, v143
	v_fmac_f32_e32 v231, v23, v159
	v_fmac_f32_e32 v228, v24, v112
	v_fmac_f32_e32 v229, v24, v128
	v_fmac_f32_e32 v230, v24, v144
	v_fmac_f32_e32 v231, v24, v160
	v_fmac_f32_e32 v228, v25, v113
	v_fmac_f32_e32 v229, v25, v129
	v_fmac_f32_e32 v230, v25, v145
	v_fmac_f32_e32 v231, v25, v161
	v_fmac_f32_e32 v228, v26, v114
	v_fmac_f32_e32 v229, v26, v130
	v_fmac_f32_e32 v230, v26, v146
	v_fmac_f32_e32 v231, v26, v162
	v_fmac_f32_e32 v228, v27, v115
	v_fmac_f32_e32 v229, v27, v131
	v_fmac_f32_e32 v230, v27, v147
	v_fmac_f32_e32 v231, v27, v163
	v_add_f32_dpp v228, v228, v228 quad_perm:[1,0,3,2] row_mask:0xf bank_mask:0xf
	v_add_f32_dpp v229, v229, v229 quad_perm:[1,0,3,2] row_mask:0xf bank_mask:0xf
	v_add_f32_dpp v230, v230, v230 quad_perm:[1,0,3,2] row_mask:0xf bank_mask:0xf
	v_add_f32_dpp v231, v231, v231 quad_perm:[1,0,3,2] row_mask:0xf bank_mask:0xf
	v_add_f32_dpp v228, v228, v228 quad_perm:[2,3,0,1] row_mask:0xf bank_mask:0xf
	v_add_f32_dpp v229, v229, v229 quad_perm:[2,3,0,1] row_mask:0xf bank_mask:0xf
	v_add_f32_dpp v230, v230, v230 quad_perm:[2,3,0,1] row_mask:0xf bank_mask:0xf
	v_add_f32_dpp v231, v231, v231 quad_perm:[2,3,0,1] row_mask:0xf bank_mask:0xf
	v_add_f32_dpp v228, v228, v228 row_half_mirror row_mask:0xf bank_mask:0xf
	v_add_f32_dpp v229, v229, v229 row_half_mirror row_mask:0xf bank_mask:0xf
	v_add_f32_dpp v230, v230, v230 row_half_mirror row_mask:0xf bank_mask:0xf
	v_add_f32_dpp v231, v231, v231 row_half_mirror row_mask:0xf bank_mask:0xf
	v_add_f32_dpp v228, v228, v228 row_mirror row_mask:0xf bank_mask:0xf
	v_add_f32_dpp v229, v229, v229 row_mirror row_mask:0xf bank_mask:0xf
	v_add_f32_dpp v230, v230, v230 row_mirror row_mask:0xf bank_mask:0xf
	v_add_f32_dpp v231, v231, v231 row_mirror row_mask:0xf bank_mask:0xf
	v_add_f32_dpp v228, v228, v228 row_bcast:15 row_mask:0xa bank_mask:0xf
	v_add_f32_dpp v229, v229, v229 row_bcast:15 row_mask:0xa bank_mask:0xf
	v_add_f32_dpp v230, v230, v230 row_bcast:15 row_mask:0xa bank_mask:0xf
	v_add_f32_dpp v231, v231, v231 row_bcast:15 row_mask:0xa bank_mask:0xf
	v_add_f32_dpp v228, v228, v228 row_bcast:31 row_mask:0xc bank_mask:0xf
	v_add_f32_dpp v229, v229, v229 row_bcast:31 row_mask:0xc bank_mask:0xf
	v_add_f32_dpp v230, v230, v230 row_bcast:31 row_mask:0xc bank_mask:0xf
	v_add_f32_dpp v231, v231, v231 row_bcast:31 row_mask:0xc bank_mask:0xf
	v_lshlrev_b32_e32 v12, 16, v48
	v_and_b32_e32 v13, 0xffff0000, v48
	v_lshlrev_b32_e32 v14, 16, v49
	v_and_b32_e32 v15, 0xffff0000, v49
	v_lshlrev_b32_e32 v16, 16, v50
	v_and_b32_e32 v17, 0xffff0000, v50
	v_lshlrev_b32_e32 v18, 16, v51
	v_and_b32_e32 v19, 0xffff0000, v51
	v_lshlrev_b32_e32 v20, 16, v52
	v_and_b32_e32 v21, 0xffff0000, v52
	v_lshlrev_b32_e32 v22, 16, v53
	v_and_b32_e32 v23, 0xffff0000, v53
	v_lshlrev_b32_e32 v24, 16, v54
	v_and_b32_e32 v25, 0xffff0000, v54
	v_lshlrev_b32_e32 v26, 16, v55
	v_and_b32_e32 v27, 0xffff0000, v55
	v_mul_f32_e32 v232, v12, v100
	v_mul_f32_e32 v233, v12, v116
	v_mul_f32_e32 v234, v12, v132
	v_mul_f32_e32 v235, v12, v148
	v_fmac_f32_e32 v232, v13, v101
	v_fmac_f32_e32 v233, v13, v117
	v_fmac_f32_e32 v234, v13, v133
	v_fmac_f32_e32 v235, v13, v149
	v_fmac_f32_e32 v232, v14, v102
	v_fmac_f32_e32 v233, v14, v118
	v_fmac_f32_e32 v234, v14, v134
	v_fmac_f32_e32 v235, v14, v150
	v_fmac_f32_e32 v232, v15, v103
	v_fmac_f32_e32 v233, v15, v119
	v_fmac_f32_e32 v234, v15, v135
	v_fmac_f32_e32 v235, v15, v151
	v_fmac_f32_e32 v232, v16, v104
	v_fmac_f32_e32 v233, v16, v120
	v_fmac_f32_e32 v234, v16, v136
	v_fmac_f32_e32 v235, v16, v152
	v_fmac_f32_e32 v232, v17, v105
	v_fmac_f32_e32 v233, v17, v121
	v_fmac_f32_e32 v234, v17, v137
; __device__ __forceinline__ void p1_rows(const Args& A, int lane, int wave) {
;     ...
;         float a0 = 0.f, a1 = 0.f, a2 = 0.f, a3 = 0.f;
; #pragma unroll
;         for (int j = 0; j < 2; ++j) { const int k = 8 * lane + 512 * j; f32x4 wa, wb; pg8::unpack8(*(const u32x4*)(wrow + k), wa, wb);
;     ...
;             BDOT(a0, 0) BDOT(a1, 1) BDOT(a2, 2) BDOT(a3, 3)
;     ...
;         }
;         a0 = wave_sum(a0); a1 = wave_sum(a1); a2 = wave_sum(a2); a3 = wave_sum(a3);
	v_fmac_f32_e32 v235, v17, v153
	v_fmac_f32_e32 v232, v18, v106
	v_fmac_f32_e32 v233, v18, v122
	v_fmac_f32_e32 v234, v18, v138
	v_fmac_f32_e32 v235, v18, v154
	v_fmac_f32_e32 v232, v19, v107
	v_fmac_f32_e32 v233, v19, v123
	v_fmac_f32_e32 v234, v19, v139
	v_fmac_f32_e32 v235, v19, v155
	v_fmac_f32_e32 v232, v20, v108
	v_fmac_f32_e32 v233, v20, v124
	v_fmac_f32_e32 v234, v20, v140
	v_fmac_f32_e32 v235, v20, v156
	v_fmac_f32_e32 v232, v21, v109
	v_fmac_f32_e32 v233, v21, v125
	v_fmac_f32_e32 v234, v21, v141
	v_fmac_f32_e32 v235, v21, v157
	v_fmac_f32_e32 v232, v22, v110
	v_fmac_f32_e32 v233, v22, v126
	v_fmac_f32_e32 v234, v22, v142
	v_fmac_f32_e32 v235, v22, v158
	v_fmac_f32_e32 v232, v23, v111
	v_fmac_f32_e32 v233, v23, v127
	v_fmac_f32_e32 v234, v23, v143
	v_fmac_f32_e32 v235, v23, v159
	v_fmac_f32_e32 v232, v24, v112
	v_fmac_f32_e32 v233, v24, v128
	v_fmac_f32_e32 v234, v24, v144
	v_fmac_f32_e32 v235, v24, v160
	v_fmac_f32_e32 v232, v25, v113
	v_fmac_f32_e32 v233, v25, v129
	v_fmac_f32_e32 v234, v25, v145
	v_fmac_f32_e32 v235, v25, v161
	v_fmac_f32_e32 v232, v26, v114
	v_fmac_f32_e32 v233, v26, v130
	v_fmac_f32_e32 v234, v26, v146
	v_fmac_f32_e32 v235, v26, v162
	v_fmac_f32_e32 v232, v27, v115
	v_fmac_f32_e32 v233, v27, v131
	v_fmac_f32_e32 v234, v27, v147
	v_fmac_f32_e32 v235, v27, v163
	v_add_f32_dpp v232, v232, v232 quad_perm:[1,0,3,2] row_mask:0xf bank_mask:0xf
	v_add_f32_dpp v233, v233, v233 quad_perm:[1,0,3,2] row_mask:0xf bank_mask:0xf
	v_add_f32_dpp v234, v234, v234 quad_perm:[1,0,3,2] row_mask:0xf bank_mask:0xf
	v_add_f32_dpp v235, v235, v235 quad_perm:[1,0,3,2] row_mask:0xf bank_mask:0xf
	v_add_f32_dpp v232, v232, v232 quad_perm:[2,3,0,1] row_mask:0xf bank_mask:0xf
	v_add_f32_dpp v233, v233, v233 quad_perm:[2,3,0,1] row_mask:0xf bank_mask:0xf
	v_add_f32_dpp v234, v234, v234 quad_perm:[2,3,0,1] row_mask:0xf bank_mask:0xf
	v_add_f32_dpp v235, v235, v235 quad_perm:[2,3,0,1] row_mask:0xf bank_mask:0xf
	v_add_f32_dpp v232, v232, v232 row_half_mirror row_mask:0xf bank_mask:0xf
	v_add_f32_dpp v233, v233, v233 row_half_mirror row_mask:0xf bank_mask:0xf
	v_add_f32_dpp v234, v234, v234 row_half_mirror row_mask:0xf bank_mask:0xf
	v_add_f32_dpp v235, v235, v235 row_half_mirror row_mask:0xf bank_mask:0xf
	v_add_f32_dpp v232, v232, v232 row_mirror row_mask:0xf bank_mask:0xf
	v_add_f32_dpp v233, v233, v233 row_mirror row_mask:0xf bank_mask:0xf
	v_add_f32_dpp v234, v234, v234 row_mirror row_mask:0xf bank_mask:0xf
	v_add_f32_dpp v235, v235, v235 row_mirror row_mask:0xf bank_mask:0xf
	v_add_f32_dpp v232, v232, v232 row_bcast:15 row_mask:0xa bank_mask:0xf
	v_add_f32_dpp v233, v233, v233 row_bcast:15 row_mask:0xa bank_mask:0xf
	v_add_f32_dpp v234, v234, v234 row_bcast:15 row_mask:0xa bank_mask:0xf
	v_add_f32_dpp v235, v235, v235 row_bcast:15 row_mask:0xa bank_mask:0xf
	v_add_f32_dpp v232, v232, v232 row_bcast:31 row_mask:0xc bank_mask:0xf
	v_add_f32_dpp v233, v233, v233 row_bcast:31 row_mask:0xc bank_mask:0xf
	v_add_f32_dpp v234, v234, v234 row_bcast:31 row_mask:0xc bank_mask:0xf
	v_add_f32_dpp v235, v235, v235 row_bcast:31 row_mask:0xc bank_mask:0xf
	v_lshlrev_b32_e32 v12, 16, v56
	v_and_b32_e32 v13, 0xffff0000, v56
	v_lshlrev_b32_e32 v14, 16, v57
	v_and_b32_e32 v15, 0xffff0000, v57
	v_lshlrev_b32_e32 v16, 16, v58
	v_and_b32_e32 v17, 0xffff0000, v58
	v_lshlrev_b32_e32 v18, 16, v59
	v_and_b32_e32 v19, 0xffff0000, v59
	v_lshlrev_b32_e32 v20, 16, v60
	v_and_b32_e32 v21, 0xffff0000, v60
	v_lshlrev_b32_e32 v22, 16, v61
	v_and_b32_e32 v23, 0xffff0000, v61
	v_lshlrev_b32_e32 v24, 16, v62
	v_and_b32_e32 v25, 0xffff0000, v62
	v_lshlrev_b32_e32 v26, 16, v63
	v_and_b32_e32 v27, 0xffff0000, v63
	v_mul_f32_e32 v236, v12, v100
	v_mul_f32_e32 v237, v12, v116
	v_mul_f32_e32 v238, v12, v132
	v_mul_f32_e32 v239, v12, v148
	v_fmac_f32_e32 v236, v13, v101
	v_fmac_f32_e32 v237, v13, v117
	v_fmac_f32_e32 v238, v13, v133
	v_fmac_f32_e32 v239, v13, v149
	v_fmac_f32_e32 v236, v14, v102
	v_fmac_f32_e32 v237, v14, v118
	v_fmac_f32_e32 v238, v14, v134
	v_fmac_f32_e32 v239, v14, v150
	v_fmac_f32_e32 v236, v15, v103
	v_fmac_f32_e32 v237, v15, v119
	v_fmac_f32_e32 v238, v15, v135
	v_fmac_f32_e32 v239, v15, v151
	v_fmac_f32_e32 v236, v16, v104
	v_fmac_f32_e32 v237, v16, v120
	v_fmac_f32_e32 v238, v16, v136
	v_fmac_f32_e32 v239, v16, v152
	v_fmac_f32_e32 v236, v17, v105
	v_fmac_f32_e32 v237, v17, v121
	v_fmac_f32_e32 v238, v17, v137
	v_fmac_f32_e32 v239, v17, v153
	v_fmac_f32_e32 v236, v18, v106
	v_fmac_f32_e32 v237, v18, v122
	v_fmac_f32_e32 v238, v18, v138
	v_fmac_f32_e32 v239, v18, v154
	v_fmac_f32_e32 v236, v19, v107
	v_fmac_f32_e32 v237, v19, v123
	v_fmac_f32_e32 v238, v19, v139
	v_fmac_f32_e32 v239, v19, v155
	v_fmac_f32_e32 v236, v20, v108
	v_fmac_f32_e32 v237, v20, v124
	v_fmac_f32_e32 v238, v20, v140
	v_fmac_f32_e32 v239, v20, v156
	v_fmac_f32_e32 v236, v21, v109
	v_fmac_f32_e32 v237, v21, v125
	v_fmac_f32_e32 v238, v21, v141
	v_fmac_f32_e32 v239, v21, v157
	v_fmac_f32_e32 v236, v22, v110
	v_fmac_f32_e32 v237, v22, v126
	v_fmac_f32_e32 v238, v22, v142
	v_fmac_f32_e32 v239, v22, v158
	v_fmac_f32_e32 v236, v23, v111
	v_fmac_f32_e32 v237, v23, v127
	v_fmac_f32_e32 v238, v23, v143
	v_fmac_f32_e32 v239, v23, v159
	v_fmac_f32_e32 v236, v24, v112
	v_fmac_f32_e32 v237, v24, v128
	v_fmac_f32_e32 v238, v24, v144
	v_fmac_f32_e32 v239, v24, v160
	v_fmac_f32_e32 v236, v25, v113
	v_fmac_f32_e32 v237, v25, v129
	v_fmac_f32_e32 v238, v25, v145
	v_fmac_f32_e32 v239, v25, v161
	v_fmac_f32_e32 v236, v26, v114
	v_fmac_f32_e32 v237, v26, v130
	v_fmac_f32_e32 v238, v26, v146
	v_fmac_f32_e32 v239, v26, v162
	v_fmac_f32_e32 v236, v27, v115
	v_fmac_f32_e32 v237, v27, v131
; __device__ __forceinline__ void p1_rows(const Args& A, int lane, int wave) {
;     ...
;         float a0 = 0.f, a1 = 0.f, a2 = 0.f, a3 = 0.f;
; #pragma unroll
;         for (int j = 0; j < 2; ++j) { const int k = 8 * lane + 512 * j; f32x4 wa, wb; pg8::unpack8(*(const u32x4*)(wrow + k), wa, wb);
;     ...
;             BDOT(a0, 0) BDOT(a1, 1) BDOT(a2, 2) BDOT(a3, 3)
;     ...
;         }
;         a0 = wave_sum(a0); a1 = wave_sum(a1); a2 = wave_sum(a2); a3 = wave_sum(a3);
	v_fmac_f32_e32 v238, v27, v147
	v_fmac_f32_e32 v239, v27, v163
	v_add_f32_dpp v236, v236, v236 quad_perm:[1,0,3,2] row_mask:0xf bank_mask:0xf
	v_add_f32_dpp v237, v237, v237 quad_perm:[1,0,3,2] row_mask:0xf bank_mask:0xf
	v_add_f32_dpp v238, v238, v238 quad_perm:[1,0,3,2] row_mask:0xf bank_mask:0xf
	v_add_f32_dpp v239, v239, v239 quad_perm:[1,0,3,2] row_mask:0xf bank_mask:0xf
	v_add_f32_dpp v236, v236, v236 quad_perm:[2,3,0,1] row_mask:0xf bank_mask:0xf
	v_add_f32_dpp v237, v237, v237 quad_perm:[2,3,0,1] row_mask:0xf bank_mask:0xf
	v_add_f32_dpp v238, v238, v238 quad_perm:[2,3,0,1] row_mask:0xf bank_mask:0xf
	v_add_f32_dpp v239, v239, v239 quad_perm:[2,3,0,1] row_mask:0xf bank_mask:0xf
	v_add_f32_dpp v236, v236, v236 row_half_mirror row_mask:0xf bank_mask:0xf
	v_add_f32_dpp v237, v237, v237 row_half_mirror row_mask:0xf bank_mask:0xf
	v_add_f32_dpp v238, v238, v238 row_half_mirror row_mask:0xf bank_mask:0xf
	v_add_f32_dpp v239, v239, v239 row_half_mirror row_mask:0xf bank_mask:0xf
	v_add_f32_dpp v236, v236, v236 row_mirror row_mask:0xf bank_mask:0xf
	v_add_f32_dpp v237, v237, v237 row_mirror row_mask:0xf bank_mask:0xf
	v_add_f32_dpp v238, v238, v238 row_mirror row_mask:0xf bank_mask:0xf
	v_add_f32_dpp v239, v239, v239 row_mirror row_mask:0xf bank_mask:0xf
	v_add_f32_dpp v236, v236, v236 row_bcast:15 row_mask:0xa bank_mask:0xf
	v_add_f32_dpp v237, v237, v237 row_bcast:15 row_mask:0xa bank_mask:0xf
	v_add_f32_dpp v238, v238, v238 row_bcast:15 row_mask:0xa bank_mask:0xf
	v_add_f32_dpp v239, v239, v239 row_bcast:15 row_mask:0xa bank_mask:0xf
	v_add_f32_dpp v236, v236, v236 row_bcast:31 row_mask:0xc bank_mask:0xf
	v_add_f32_dpp v237, v237, v237 row_bcast:31 row_mask:0xc bank_mask:0xf
	v_add_f32_dpp v238, v238, v238 row_bcast:31 row_mask:0xc bank_mask:0xf
	v_add_f32_dpp v239, v239, v239 row_bcast:31 row_mask:0xc bank_mask:0xf
	s_add_i32 s0, s6, s8
	s_add_i32 s0, s0, s8
	s_add_i32 s0, s0, s8
	s_cmpk_gt_i32 s0, 0x19ff
	s_cbranch_scc1 .Lp1b_r3b
	v_lshlrev_b32_e32 v12, 16, v64
	v_and_b32_e32 v13, 0xffff0000, v64
	v_lshlrev_b32_e32 v14, 16, v65
	v_and_b32_e32 v15, 0xffff0000, v65
	v_lshlrev_b32_e32 v16, 16, v66
	v_and_b32_e32 v17, 0xffff0000, v66
	v_lshlrev_b32_e32 v18, 16, v67
	v_and_b32_e32 v19, 0xffff0000, v67
	v_lshlrev_b32_e32 v20, 16, v68
	v_and_b32_e32 v21, 0xffff0000, v68
	v_lshlrev_b32_e32 v22, 16, v69
	v_and_b32_e32 v23, 0xffff0000, v69
	v_lshlrev_b32_e32 v24, 16, v70
	v_and_b32_e32 v25, 0xffff0000, v70
	v_lshlrev_b32_e32 v26, 16, v71
	v_and_b32_e32 v27, 0xffff0000, v71
	v_mul_f32_e32 v240, v12, v100
	v_mul_f32_e32 v241, v12, v116
	v_mul_f32_e32 v242, v12, v132
	v_mul_f32_e32 v243, v12, v148
	v_fmac_f32_e32 v240, v13, v101
	v_fmac_f32_e32 v241, v13, v117
	v_fmac_f32_e32 v242, v13, v133
	v_fmac_f32_e32 v243, v13, v149
	v_fmac_f32_e32 v240, v14, v102
	v_fmac_f32_e32 v241, v14, v118
	v_fmac_f32_e32 v242, v14, v134
	v_fmac_f32_e32 v243, v14, v150
	v_fmac_f32_e32 v240, v15, v103
	v_fmac_f32_e32 v241, v15, v119
	v_fmac_f32_e32 v242, v15, v135
	v_fmac_f32_e32 v243, v15, v151
	v_fmac_f32_e32 v240, v16, v104
	v_fmac_f32_e32 v241, v16, v120
	v_fmac_f32_e32 v242, v16, v136
	v_fmac_f32_e32 v243, v16, v152
	v_fmac_f32_e32 v240, v17, v105
	v_fmac_f32_e32 v241, v17, v121
	v_fmac_f32_e32 v242, v17, v137
	v_fmac_f32_e32 v243, v17, v153
	v_fmac_f32_e32 v240, v18, v106
	v_fmac_f32_e32 v241, v18, v122
	v_fmac_f32_e32 v242, v18, v138
	v_fmac_f32_e32 v243, v18, v154
	v_fmac_f32_e32 v240, v19, v107
	v_fmac_f32_e32 v241, v19, v123
	v_fmac_f32_e32 v242, v19, v139
	v_fmac_f32_e32 v243, v19, v155
	v_fmac_f32_e32 v240, v20, v108
	v_fmac_f32_e32 v241, v20, v124
	v_fmac_f32_e32 v242, v20, v140
	v_fmac_f32_e32 v243, v20, v156
	v_fmac_f32_e32 v240, v21, v109
	v_fmac_f32_e32 v241, v21, v125
	v_fmac_f32_e32 v242, v21, v141
	v_fmac_f32_e32 v243, v21, v157
	v_fmac_f32_e32 v240, v22, v110
	v_fmac_f32_e32 v241, v22, v126
	v_fmac_f32_e32 v242, v22, v142
	v_fmac_f32_e32 v243, v22, v158
	v_fmac_f32_e32 v240, v23, v111
	v_fmac_f32_e32 v241, v23, v127
	v_fmac_f32_e32 v242, v23, v143
	v_fmac_f32_e32 v243, v23, v159
	v_fmac_f32_e32 v240, v24, v112
	v_fmac_f32_e32 v241, v24, v128
	v_fmac_f32_e32 v242, v24, v144
	v_fmac_f32_e32 v243, v24, v160
	v_fmac_f32_e32 v240, v25, v113
	v_fmac_f32_e32 v241, v25, v129
	v_fmac_f32_e32 v242, v25, v145
	v_fmac_f32_e32 v243, v25, v161
	v_fmac_f32_e32 v240, v26, v114
	v_fmac_f32_e32 v241, v26, v130
	v_fmac_f32_e32 v242, v26, v146
	v_fmac_f32_e32 v243, v26, v162
	v_fmac_f32_e32 v240, v27, v115
	v_fmac_f32_e32 v241, v27, v131
	v_fmac_f32_e32 v242, v27, v147
	v_fmac_f32_e32 v243, v27, v163
	v_add_f32_dpp v240, v240, v240 quad_perm:[1,0,3,2] row_mask:0xf bank_mask:0xf
	v_add_f32_dpp v241, v241, v241 quad_perm:[1,0,3,2] row_mask:0xf bank_mask:0xf
	v_add_f32_dpp v242, v242, v242 quad_perm:[1,0,3,2] row_mask:0xf bank_mask:0xf
	v_add_f32_dpp v243, v243, v243 quad_perm:[1,0,3,2] row_mask:0xf bank_mask:0xf
	v_add_f32_dpp v240, v240, v240 quad_perm:[2,3,0,1] row_mask:0xf bank_mask:0xf
	v_add_f32_dpp v241, v241, v241 quad_perm:[2,3,0,1] row_mask:0xf bank_mask:0xf
	v_add_f32_dpp v242, v242, v242 quad_perm:[2,3,0,1] row_mask:0xf bank_mask:0xf
	v_add_f32_dpp v243, v243, v243 quad_perm:[2,3,0,1] row_mask:0xf bank_mask:0xf
	v_add_f32_dpp v240, v240, v240 row_half_mirror row_mask:0xf bank_mask:0xf
	v_add_f32_dpp v241, v241, v241 row_half_mirror row_mask:0xf bank_mask:0xf
	v_add_f32_dpp v242, v242, v242 row_half_mirror row_mask:0xf bank_mask:0xf
	v_add_f32_dpp v243, v243, v243 row_half_mirror row_mask:0xf bank_mask:0xf
	v_add_f32_dpp v240, v240, v240 row_mirror row_mask:0xf bank_mask:0xf
	v_add_f32_dpp v241, v241, v241 row_mirror row_mask:0xf bank_mask:0xf
	v_add_f32_dpp v242, v242, v242 row_mirror row_mask:0xf bank_mask:0xf
	v_add_f32_dpp v243, v243, v243 row_mirror row_mask:0xf bank_mask:0xf
	v_add_f32_dpp v240, v240, v240 row_bcast:15 row_mask:0xa bank_mask:0xf
	v_add_f32_dpp v241, v241, v241 row_bcast:15 row_mask:0xa bank_mask:0xf
	v_add_f32_dpp v242, v242, v242 row_bcast:15 row_mask:0xa bank_mask:0xf
	v_add_f32_dpp v243, v243, v243 row_bcast:15 row_mask:0xa bank_mask:0xf
	v_add_f32_dpp v240, v240, v240 row_bcast:31 row_mask:0xc bank_mask:0xf
	v_add_f32_dpp v241, v241, v241 row_bcast:31 row_mask:0xc bank_mask:0xf
	v_add_f32_dpp v242, v242, v242 row_bcast:31 row_mask:0xc bank_mask:0xf
	v_add_f32_dpp v243, v243, v243 row_bcast:31 row_mask:0xc bank_mask:0xf
	s_waitcnt vmcnt(0)
	s_branch .Lp1b_r3d
; __device__ __forceinline__ void p1_rows(const Args& A, int lane, int wave) {
;     ...
;         float a0 = 0.f, a1 = 0.f, a2 = 0.f, a3 = 0.f;
; #pragma unroll
;         for (int j = 0; j < 2; ++j) { const int k = 8 * lane + 512 * j; f32x4 wa, wb; pg8::unpack8(*(const u32x4*)(wrow + k), wa, wb);
;     ...
;             BDOT(a0, 0) BDOT(a1, 1) BDOT(a2, 2) BDOT(a3, 3)
;     ...
;         }
;         a0 = wave_sum(a0); a1 = wave_sum(a1); a2 = wave_sum(a2); a3 = wave_sum(a3);
.Lp1b_r3b:
	s_waitcnt vmcnt(0)
	v_lshlrev_b32_e32 v12, 16, v64
	v_and_b32_e32 v13, 0xffff0000, v64
	v_lshlrev_b32_e32 v14, 16, v65
	v_and_b32_e32 v15, 0xffff0000, v65
	v_lshlrev_b32_e32 v16, 16, v66
	v_and_b32_e32 v17, 0xffff0000, v66
	v_lshlrev_b32_e32 v18, 16, v67
	v_and_b32_e32 v19, 0xffff0000, v67
	v_lshlrev_b32_e32 v20, 16, v68
	v_and_b32_e32 v21, 0xffff0000, v68
	v_lshlrev_b32_e32 v22, 16, v69
	v_and_b32_e32 v23, 0xffff0000, v69
	v_lshlrev_b32_e32 v24, 16, v70
	v_and_b32_e32 v25, 0xffff0000, v70
	v_lshlrev_b32_e32 v26, 16, v71
	v_and_b32_e32 v27, 0xffff0000, v71
	v_mul_f32_e32 v240, v12, v164
	v_mul_f32_e32 v241, v12, v180
	v_mul_f32_e32 v242, v12, v196
	v_mul_f32_e32 v243, v12, v212
	v_fmac_f32_e32 v240, v13, v165
	v_fmac_f32_e32 v241, v13, v181
	v_fmac_f32_e32 v242, v13, v197
	v_fmac_f32_e32 v243, v13, v213
	v_fmac_f32_e32 v240, v14, v166
	v_fmac_f32_e32 v241, v14, v182
	v_fmac_f32_e32 v242, v14, v198
	v_fmac_f32_e32 v243, v14, v214
	v_fmac_f32_e32 v240, v15, v167
	v_fmac_f32_e32 v241, v15, v183
	v_fmac_f32_e32 v242, v15, v199
	v_fmac_f32_e32 v243, v15, v215
	v_fmac_f32_e32 v240, v16, v168
	v_fmac_f32_e32 v241, v16, v184
	v_fmac_f32_e32 v242, v16, v200
	v_fmac_f32_e32 v243, v16, v216
	v_fmac_f32_e32 v240, v17, v169
	v_fmac_f32_e32 v241, v17, v185
	v_fmac_f32_e32 v242, v17, v201
	v_fmac_f32_e32 v243, v17, v217
	v_fmac_f32_e32 v240, v18, v170
	v_fmac_f32_e32 v241, v18, v186
	v_fmac_f32_e32 v242, v18, v202
	v_fmac_f32_e32 v243, v18, v218
	v_fmac_f32_e32 v240, v19, v171
	v_fmac_f32_e32 v241, v19, v187
	v_fmac_f32_e32 v242, v19, v203
	v_fmac_f32_e32 v243, v19, v219
	v_fmac_f32_e32 v240, v20, v172
	v_fmac_f32_e32 v241, v20, v188
	v_fmac_f32_e32 v242, v20, v204
	v_fmac_f32_e32 v243, v20, v88
	v_fmac_f32_e32 v240, v21, v173
	v_fmac_f32_e32 v241, v21, v189
	v_fmac_f32_e32 v242, v21, v205
	v_fmac_f32_e32 v243, v21, v89
	v_fmac_f32_e32 v240, v22, v174
	v_fmac_f32_e32 v241, v22, v190
	v_fmac_f32_e32 v242, v22, v206
	v_fmac_f32_e32 v243, v22, v90
	v_fmac_f32_e32 v240, v23, v175
	v_fmac_f32_e32 v241, v23, v191
	v_fmac_f32_e32 v242, v23, v207
	v_fmac_f32_e32 v243, v23, v91
	v_fmac_f32_e32 v240, v24, v176
	v_fmac_f32_e32 v241, v24, v192
	v_fmac_f32_e32 v242, v24, v208
	v_fmac_f32_e32 v243, v24, v92
	v_fmac_f32_e32 v240, v25, v177
	v_fmac_f32_e32 v241, v25, v193
	v_fmac_f32_e32 v242, v25, v209
	v_fmac_f32_e32 v243, v25, v93
	v_fmac_f32_e32 v240, v26, v178
	v_fmac_f32_e32 v241, v26, v194
	v_fmac_f32_e32 v242, v26, v210
	v_fmac_f32_e32 v243, v26, v94
	v_fmac_f32_e32 v240, v27, v179
	v_fmac_f32_e32 v241, v27, v195
	v_fmac_f32_e32 v242, v27, v211
	v_fmac_f32_e32 v243, v27, v95
	v_add_f32_dpp v240, v240, v240 quad_perm:[1,0,3,2] row_mask:0xf bank_mask:0xf
	v_add_f32_dpp v241, v241, v241 quad_perm:[1,0,3,2] row_mask:0xf bank_mask:0xf
	v_add_f32_dpp v242, v242, v242 quad_perm:[1,0,3,2] row_mask:0xf bank_mask:0xf
	v_add_f32_dpp v243, v243, v243 quad_perm:[1,0,3,2] row_mask:0xf bank_mask:0xf
	v_add_f32_dpp v240, v240, v240 quad_perm:[2,3,0,1] row_mask:0xf bank_mask:0xf
	v_add_f32_dpp v241, v241, v241 quad_perm:[2,3,0,1] row_mask:0xf bank_mask:0xf
	v_add_f32_dpp v242, v242, v242 quad_perm:[2,3,0,1] row_mask:0xf bank_mask:0xf
	v_add_f32_dpp v243, v243, v243 quad_perm:[2,3,0,1] row_mask:0xf bank_mask:0xf
	v_add_f32_dpp v240, v240, v240 row_half_mirror row_mask:0xf bank_mask:0xf
	v_add_f32_dpp v241, v241, v241 row_half_mirror row_mask:0xf bank_mask:0xf
	v_add_f32_dpp v242, v242, v242 row_half_mirror row_mask:0xf bank_mask:0xf
	v_add_f32_dpp v243, v243, v243 row_half_mirror row_mask:0xf bank_mask:0xf
	v_add_f32_dpp v240, v240, v240 row_mirror row_mask:0xf bank_mask:0xf
	v_add_f32_dpp v241, v241, v241 row_mirror row_mask:0xf bank_mask:0xf
	v_add_f32_dpp v242, v242, v242 row_mirror row_mask:0xf bank_mask:0xf
	v_add_f32_dpp v243, v243, v243 row_mirror row_mask:0xf bank_mask:0xf
	v_add_f32_dpp v240, v240, v240 row_bcast:15 row_mask:0xa bank_mask:0xf
	v_add_f32_dpp v241, v241, v241 row_bcast:15 row_mask:0xa bank_mask:0xf
	v_add_f32_dpp v242, v242, v242 row_bcast:15 row_mask:0xa bank_mask:0xf
	v_add_f32_dpp v243, v243, v243 row_bcast:15 row_mask:0xa bank_mask:0xf
	v_add_f32_dpp v240, v240, v240 row_bcast:31 row_mask:0xc bank_mask:0xf
	v_add_f32_dpp v241, v241, v241 row_bcast:31 row_mask:0xc bank_mask:0xf
	v_add_f32_dpp v242, v242, v242 row_bcast:31 row_mask:0xc bank_mask:0xf
	v_add_f32_dpp v243, v243, v243 row_bcast:31 row_mask:0xc bank_mask:0xf
; __device__ __forceinline__ void p1_rows(const Args& A, int lane, int wave) {
;     ...
;         float a0 = 0.f, a1 = 0.f, a2 = 0.f, a3 = 0.f;
; #pragma unroll
;         for (int j = 0; j < 2; ++j) { const int k = 8 * lane + 512 * j; f32x4 wa, wb; pg8::unpack8(*(const u32x4*)(wrow + k), wa, wb);
;     ...
;             BDOT(a0, 0) BDOT(a1, 1) BDOT(a2, 2) BDOT(a3, 3)
;     ...
;         }
;         a0 = wave_sum(a0); a1 = wave_sum(a1); a2 = wave_sum(a2); a3 = wave_sum(a3);
.Lp1b_r3d:
	v_lshlrev_b32_e32 v12, 16, v72
	v_and_b32_e32 v13, 0xffff0000, v72
	v_lshlrev_b32_e32 v14, 16, v73
	v_and_b32_e32 v15, 0xffff0000, v73
	v_lshlrev_b32_e32 v16, 16, v74
	v_and_b32_e32 v17, 0xffff0000, v74
	v_lshlrev_b32_e32 v18, 16, v75
	v_and_b32_e32 v19, 0xffff0000, v75
	v_lshlrev_b32_e32 v20, 16, v76
	v_and_b32_e32 v21, 0xffff0000, v76
	v_lshlrev_b32_e32 v22, 16, v77
	v_and_b32_e32 v23, 0xffff0000, v77
	v_lshlrev_b32_e32 v24, 16, v78
	v_and_b32_e32 v25, 0xffff0000, v78
	v_lshlrev_b32_e32 v26, 16, v79
	v_and_b32_e32 v27, 0xffff0000, v79
	v_mul_f32_e32 v244, v12, v164
	v_mul_f32_e32 v245, v12, v180
	v_mul_f32_e32 v246, v12, v196
	v_mul_f32_e32 v247, v12, v212
	v_fmac_f32_e32 v244, v13, v165
	v_fmac_f32_e32 v245, v13, v181
	v_fmac_f32_e32 v246, v13, v197
	v_fmac_f32_e32 v247, v13, v213
	v_fmac_f32_e32 v244, v14, v166
	v_fmac_f32_e32 v245, v14, v182
	v_fmac_f32_e32 v246, v14, v198
	v_fmac_f32_e32 v247, v14, v214
	v_fmac_f32_e32 v244, v15, v167
	v_fmac_f32_e32 v245, v15, v183
	v_fmac_f32_e32 v246, v15, v199
	v_fmac_f32_e32 v247, v15, v215
	v_fmac_f32_e32 v244, v16, v168
	v_fmac_f32_e32 v245, v16, v184
	v_fmac_f32_e32 v246, v16, v200
	v_fmac_f32_e32 v247, v16, v216
	v_fmac_f32_e32 v244, v17, v169
	v_fmac_f32_e32 v245, v17, v185
	v_fmac_f32_e32 v246, v17, v201
	v_fmac_f32_e32 v247, v17, v217
	v_fmac_f32_e32 v244, v18, v170
	v_fmac_f32_e32 v245, v18, v186
	v_fmac_f32_e32 v246, v18, v202
	v_fmac_f32_e32 v247, v18, v218
	v_fmac_f32_e32 v244, v19, v171
	v_fmac_f32_e32 v245, v19, v187
	v_fmac_f32_e32 v246, v19, v203
	v_fmac_f32_e32 v247, v19, v219
	v_fmac_f32_e32 v244, v20, v172
	v_fmac_f32_e32 v245, v20, v188
	v_fmac_f32_e32 v246, v20, v204
	v_fmac_f32_e32 v247, v20, v88
	v_fmac_f32_e32 v244, v21, v173
	v_fmac_f32_e32 v245, v21, v189
	v_fmac_f32_e32 v246, v21, v205
	v_fmac_f32_e32 v247, v21, v89
	v_fmac_f32_e32 v244, v22, v174
	v_fmac_f32_e32 v245, v22, v190
	v_fmac_f32_e32 v246, v22, v206
	v_fmac_f32_e32 v247, v22, v90
	v_fmac_f32_e32 v244, v23, v175
	v_fmac_f32_e32 v245, v23, v191
	v_fmac_f32_e32 v246, v23, v207
	v_fmac_f32_e32 v247, v23, v91
	v_fmac_f32_e32 v244, v24, v176
	v_fmac_f32_e32 v245, v24, v192
	v_fmac_f32_e32 v246, v24, v208
	v_fmac_f32_e32 v247, v24, v92
	v_fmac_f32_e32 v244, v25, v177
	v_fmac_f32_e32 v245, v25, v193
	v_fmac_f32_e32 v246, v25, v209
	v_fmac_f32_e32 v247, v25, v93
	v_fmac_f32_e32 v244, v26, v178
	v_fmac_f32_e32 v245, v26, v194
	v_fmac_f32_e32 v246, v26, v210
	v_fmac_f32_e32 v247, v26, v94
	v_fmac_f32_e32 v244, v27, v179
	v_fmac_f32_e32 v245, v27, v195
	v_fmac_f32_e32 v246, v27, v211
	v_fmac_f32_e32 v247, v27, v95
	v_add_f32_dpp v244, v244, v244 quad_perm:[1,0,3,2] row_mask:0xf bank_mask:0xf
	v_add_f32_dpp v245, v245, v245 quad_perm:[1,0,3,2] row_mask:0xf bank_mask:0xf
	v_add_f32_dpp v246, v246, v246 quad_perm:[1,0,3,2] row_mask:0xf bank_mask:0xf
	v_add_f32_dpp v247, v247, v247 quad_perm:[1,0,3,2] row_mask:0xf bank_mask:0xf
	v_add_f32_dpp v244, v244, v244 quad_perm:[2,3,0,1] row_mask:0xf bank_mask:0xf
	v_add_f32_dpp v245, v245, v245 quad_perm:[2,3,0,1] row_mask:0xf bank_mask:0xf
	v_add_f32_dpp v246, v246, v246 quad_perm:[2,3,0,1] row_mask:0xf bank_mask:0xf
	v_add_f32_dpp v247, v247, v247 quad_perm:[2,3,0,1] row_mask:0xf bank_mask:0xf
	v_add_f32_dpp v244, v244, v244 row_half_mirror row_mask:0xf bank_mask:0xf
	v_add_f32_dpp v245, v245, v245 row_half_mirror row_mask:0xf bank_mask:0xf
	v_add_f32_dpp v246, v246, v246 row_half_mirror row_mask:0xf bank_mask:0xf
	v_add_f32_dpp v247, v247, v247 row_half_mirror row_mask:0xf bank_mask:0xf
	v_add_f32_dpp v244, v244, v244 row_mirror row_mask:0xf bank_mask:0xf
	v_add_f32_dpp v245, v245, v245 row_mirror row_mask:0xf bank_mask:0xf
	v_add_f32_dpp v246, v246, v246 row_mirror row_mask:0xf bank_mask:0xf
	v_add_f32_dpp v247, v247, v247 row_mirror row_mask:0xf bank_mask:0xf
	v_add_f32_dpp v244, v244, v244 row_bcast:15 row_mask:0xa bank_mask:0xf
	v_add_f32_dpp v245, v245, v245 row_bcast:15 row_mask:0xa bank_mask:0xf
	v_add_f32_dpp v246, v246, v246 row_bcast:15 row_mask:0xa bank_mask:0xf
	v_add_f32_dpp v247, v247, v247 row_bcast:15 row_mask:0xa bank_mask:0xf
	v_add_f32_dpp v244, v244, v244 row_bcast:31 row_mask:0xc bank_mask:0xf
	v_add_f32_dpp v245, v245, v245 row_bcast:31 row_mask:0xc bank_mask:0xf
	v_add_f32_dpp v246, v246, v246 row_bcast:31 row_mask:0xc bank_mask:0xf
	v_add_f32_dpp v247, v247, v247 row_bcast:31 row_mask:0xc bank_mask:0xf
	v_lshlrev_b32_e32 v12, 16, v80
	v_and_b32_e32 v13, 0xffff0000, v80
	v_lshlrev_b32_e32 v14, 16, v81
	v_and_b32_e32 v15, 0xffff0000, v81
	v_lshlrev_b32_e32 v16, 16, v82
	v_and_b32_e32 v17, 0xffff0000, v82
	v_lshlrev_b32_e32 v18, 16, v83
	v_and_b32_e32 v19, 0xffff0000, v83
	v_lshlrev_b32_e32 v20, 16, v84
	v_and_b32_e32 v21, 0xffff0000, v84
	v_lshlrev_b32_e32 v22, 16, v85
	v_and_b32_e32 v23, 0xffff0000, v85
	v_lshlrev_b32_e32 v24, 16, v86
	v_and_b32_e32 v25, 0xffff0000, v86
	v_lshlrev_b32_e32 v26, 16, v87
	v_and_b32_e32 v27, 0xffff0000, v87
	v_mul_f32_e32 v248, v12, v164
	v_mul_f32_e32 v249, v12, v180
	v_mul_f32_e32 v250, v12, v196
	v_mul_f32_e32 v251, v12, v212
	v_fmac_f32_e32 v248, v13, v165
	v_fmac_f32_e32 v249, v13, v181
	v_fmac_f32_e32 v250, v13, v197
	v_fmac_f32_e32 v251, v13, v213
	v_fmac_f32_e32 v248, v14, v166
	v_fmac_f32_e32 v249, v14, v182
	v_fmac_f32_e32 v250, v14, v198
	v_fmac_f32_e32 v251, v14, v214
	v_fmac_f32_e32 v248, v15, v167
	v_fmac_f32_e32 v249, v15, v183
	v_fmac_f32_e32 v250, v15, v199
	v_fmac_f32_e32 v251, v15, v215
	v_fmac_f32_e32 v248, v16, v168
	v_fmac_f32_e32 v249, v16, v184
	v_fmac_f32_e32 v250, v16, v200
	v_fmac_f32_e32 v251, v16, v216
	v_fmac_f32_e32 v248, v17, v169
	v_fmac_f32_e32 v249, v17, v185
	v_fmac_f32_e32 v250, v17, v201
; __device__ __forceinline__ void p1_rows(const Args& A, int lane, int wave) {
;     ...
;         a0 = wave_sum(a0); a1 = wave_sum(a1); a2 = wave_sum(a2); a3 = wave_sum(a3);
;         if (lane == 0) { float* bo = (float*)(ws + (second ? WS_BIAS3 : WS_BIAS2)); const int N = second ? NGU : DIN;
;             bo[dr] = a0; bo[N + dr] = a1; bo[2 * N + dr] = a2; bo[3 * N + dr] = a3; }
	v_fmac_f32_e32 v251, v17, v217
	v_fmac_f32_e32 v248, v18, v170
	v_fmac_f32_e32 v249, v18, v186
	v_fmac_f32_e32 v250, v18, v202
	v_fmac_f32_e32 v251, v18, v218
	v_fmac_f32_e32 v248, v19, v171
	v_fmac_f32_e32 v249, v19, v187
	v_fmac_f32_e32 v250, v19, v203
	v_fmac_f32_e32 v251, v19, v219
	v_fmac_f32_e32 v248, v20, v172
	v_fmac_f32_e32 v249, v20, v188
	v_fmac_f32_e32 v250, v20, v204
	v_fmac_f32_e32 v251, v20, v88
	v_fmac_f32_e32 v248, v21, v173
	v_fmac_f32_e32 v249, v21, v189
	v_fmac_f32_e32 v250, v21, v205
	v_fmac_f32_e32 v251, v21, v89
	v_fmac_f32_e32 v248, v22, v174
	v_fmac_f32_e32 v249, v22, v190
	v_fmac_f32_e32 v250, v22, v206
	v_fmac_f32_e32 v251, v22, v90
	v_fmac_f32_e32 v248, v23, v175
	v_fmac_f32_e32 v249, v23, v191
	v_fmac_f32_e32 v250, v23, v207
	v_fmac_f32_e32 v251, v23, v91
	v_fmac_f32_e32 v248, v24, v176
	v_fmac_f32_e32 v249, v24, v192
	v_fmac_f32_e32 v250, v24, v208
	v_fmac_f32_e32 v251, v24, v92
	v_fmac_f32_e32 v248, v25, v177
	v_fmac_f32_e32 v249, v25, v193
	v_fmac_f32_e32 v250, v25, v209
	v_fmac_f32_e32 v251, v25, v93
	v_fmac_f32_e32 v248, v26, v178
	v_fmac_f32_e32 v249, v26, v194
	v_fmac_f32_e32 v250, v26, v210
	v_fmac_f32_e32 v251, v26, v94
	v_fmac_f32_e32 v248, v27, v179
	v_fmac_f32_e32 v249, v27, v195
	v_fmac_f32_e32 v250, v27, v211
	v_fmac_f32_e32 v251, v27, v95
	v_add_f32_dpp v248, v248, v248 quad_perm:[1,0,3,2] row_mask:0xf bank_mask:0xf
	v_add_f32_dpp v249, v249, v249 quad_perm:[1,0,3,2] row_mask:0xf bank_mask:0xf
	v_add_f32_dpp v250, v250, v250 quad_perm:[1,0,3,2] row_mask:0xf bank_mask:0xf
	v_add_f32_dpp v251, v251, v251 quad_perm:[1,0,3,2] row_mask:0xf bank_mask:0xf
	v_add_f32_dpp v248, v248, v248 quad_perm:[2,3,0,1] row_mask:0xf bank_mask:0xf
	v_add_f32_dpp v249, v249, v249 quad_perm:[2,3,0,1] row_mask:0xf bank_mask:0xf
	v_add_f32_dpp v250, v250, v250 quad_perm:[2,3,0,1] row_mask:0xf bank_mask:0xf
	v_add_f32_dpp v251, v251, v251 quad_perm:[2,3,0,1] row_mask:0xf bank_mask:0xf
	v_add_f32_dpp v248, v248, v248 row_half_mirror row_mask:0xf bank_mask:0xf
	v_add_f32_dpp v249, v249, v249 row_half_mirror row_mask:0xf bank_mask:0xf
	v_add_f32_dpp v250, v250, v250 row_half_mirror row_mask:0xf bank_mask:0xf
	v_add_f32_dpp v251, v251, v251 row_half_mirror row_mask:0xf bank_mask:0xf
	v_add_f32_dpp v248, v248, v248 row_mirror row_mask:0xf bank_mask:0xf
	v_add_f32_dpp v249, v249, v249 row_mirror row_mask:0xf bank_mask:0xf
	v_add_f32_dpp v250, v250, v250 row_mirror row_mask:0xf bank_mask:0xf
	v_add_f32_dpp v251, v251, v251 row_mirror row_mask:0xf bank_mask:0xf
	v_add_f32_dpp v248, v248, v248 row_bcast:15 row_mask:0xa bank_mask:0xf
	v_add_f32_dpp v249, v249, v249 row_bcast:15 row_mask:0xa bank_mask:0xf
	v_add_f32_dpp v250, v250, v250 row_bcast:15 row_mask:0xa bank_mask:0xf
	v_add_f32_dpp v251, v251, v251 row_bcast:15 row_mask:0xa bank_mask:0xf
	v_add_f32_dpp v248, v248, v248 row_bcast:31 row_mask:0xc bank_mask:0xf
	v_add_f32_dpp v249, v249, v249 row_bcast:31 row_mask:0xc bank_mask:0xf
	v_add_f32_dpp v250, v250, v250 row_bcast:31 row_mask:0xc bank_mask:0xf
	v_add_f32_dpp v251, v251, v251 row_bcast:31 row_mask:0xc bank_mask:0xf
	v_mov_b32_e32 v7, 0
	s_mov_b32 exec_lo, 0
	s_mov_b32 exec_hi, 0x80000000
	s_mov_b32 s14, 0x60000
	s_mov_b32 s15, 0x40000
	s_movk_i32 s18, 0x5800
	s_movk_i32 s19, 0x6800
	s_mov_b32 s0, s6
	s_add_i32 s9, s0, 0xffffe600
	s_cmpk_gt_i32 s0, 0x19ff
	s_cselect_b32 s9, s9, s0
	s_cselect_b32 s1, s14, s15
	s_cselect_b32 s10, s18, s19
	s_lshl_b32 s9, s9, 2
	s_add_u32 s12, s4, s1
	s_addc_u32 s13, s5, 0
	s_add_u32 s12, s12, s9
	s_addc_u32 s13, s13, 0
	s_lshl_b32 s11, s10, 1
	v_mov_b32_e32 v8, s10
	s_add_i32 s10, s11, s10
	v_mov_b32_e32 v9, s11
	v_mov_b32_e32 v10, s10
	global_store_dword v7, v228, s[12:13]
	global_store_dword v8, v229, s[12:13]
	global_store_dword v9, v230, s[12:13]
	global_store_dword v10, v231, s[12:13]
	s_add_i32 s0, s0, s8
	s_add_i32 s9, s0, 0xffffe600
	s_cmpk_gt_i32 s0, 0x19ff
	s_cselect_b32 s9, s9, s0
	s_cselect_b32 s1, s14, s15
	s_cselect_b32 s10, s18, s19
	s_lshl_b32 s9, s9, 2
	s_add_u32 s12, s4, s1
	s_addc_u32 s13, s5, 0
	s_add_u32 s12, s12, s9
	s_addc_u32 s13, s13, 0
	s_lshl_b32 s11, s10, 1
	v_mov_b32_e32 v8, s10
	s_add_i32 s10, s11, s10
	v_mov_b32_e32 v9, s11
	v_mov_b32_e32 v10, s10
	global_store_dword v7, v232, s[12:13]
	global_store_dword v8, v233, s[12:13]
	global_store_dword v9, v234, s[12:13]
	global_store_dword v10, v235, s[12:13]
	s_add_i32 s0, s0, s8
	s_add_i32 s9, s0, 0xffffe600
	s_cmpk_gt_i32 s0, 0x19ff
	s_cselect_b32 s9, s9, s0
	s_cselect_b32 s1, s14, s15
	s_cselect_b32 s10, s18, s19
	s_lshl_b32 s9, s9, 2
	s_add_u32 s12, s4, s1
	s_addc_u32 s13, s5, 0
	s_add_u32 s12, s12, s9
	s_addc_u32 s13, s13, 0
	s_lshl_b32 s11, s10, 1
	v_mov_b32_e32 v8, s10
	s_add_i32 s10, s11, s10
	v_mov_b32_e32 v9, s11
	v_mov_b32_e32 v10, s10
	global_store_dword v7, v236, s[12:13]
	global_store_dword v8, v237, s[12:13]
	global_store_dword v9, v238, s[12:13]
	global_store_dword v10, v239, s[12:13]
	s_add_i32 s0, s0, s8
	s_add_i32 s9, s0, 0xffffe600
	s_cmpk_gt_i32 s0, 0x19ff
	s_cselect_b32 s9, s9, s0
	s_cselect_b32 s1, s14, s15
	s_cselect_b32 s10, s18, s19
	s_lshl_b32 s9, s9, 2
	s_add_u32 s12, s4, s1
	s_addc_u32 s13, s5, 0
	s_add_u32 s12, s12, s9
	s_addc_u32 s13, s13, 0
	s_lshl_b32 s11, s10, 1
	v_mov_b32_e32 v8, s10
	s_add_i32 s10, s11, s10
	v_mov_b32_e32 v9, s11
	v_mov_b32_e32 v10, s10
	global_store_dword v7, v240, s[12:13]
	global_store_dword v8, v241, s[12:13]
	global_store_dword v9, v242, s[12:13]
	global_store_dword v10, v243, s[12:13]
	s_add_i32 s0, s0, s8
	s_add_i32 s9, s0, 0xffffe600
	s_cmpk_gt_i32 s0, 0x19ff
	s_cselect_b32 s9, s9, s0
	s_cselect_b32 s1, s14, s15
	s_cselect_b32 s10, s18, s19
	s_lshl_b32 s9, s9, 2
	s_add_u32 s12, s4, s1
	s_addc_u32 s13, s5, 0
	s_add_u32 s12, s12, s9
	s_addc_u32 s13, s13, 0
	s_lshl_b32 s11, s10, 1
	v_mov_b32_e32 v8, s10
	s_add_i32 s10, s11, s10
	v_mov_b32_e32 v9, s11
	v_mov_b32_e32 v10, s10
	global_store_dword v7, v244, s[12:13]
	global_store_dword v8, v245, s[12:13]
	global_store_dword v9, v246, s[12:13]
	global_store_dword v10, v247, s[12:13]
	s_add_i32 s0, s0, s8
	s_add_i32 s9, s0, 0xffffe600
	s_cmpk_gt_i32 s0, 0x19ff
	s_cselect_b32 s9, s9, s0
	s_cselect_b32 s1, s14, s15
	s_cselect_b32 s10, s18, s19
	s_lshl_b32 s9, s9, 2
	s_add_u32 s12, s4, s1
	s_addc_u32 s13, s5, 0
	s_add_u32 s12, s12, s9
	s_addc_u32 s13, s13, 0
	s_lshl_b32 s11, s10, 1
	v_mov_b32_e32 v8, s10
	s_add_i32 s10, s11, s10
	v_mov_b32_e32 v9, s11
	v_mov_b32_e32 v10, s10
	global_store_dword v7, v248, s[12:13]
	global_store_dword v8, v249, s[12:13]
	global_store_dword v9, v250, s[12:13]
	global_store_dword v10, v251, s[12:13]
	s_mov_b64 exec, -1
